# v52 + rstd2 loads in the down-proj epilogue and P8 made agent-coherent (sc1) so the acquire-invalidate after the up-proj phase is no longer needed and is removed
# baseline (speedup 1.0000x reference)
; DI float bflo(unsigned u) { return __uint_as_float(u << 16); }
; DI float bfhi(unsigned u) { return __uint_as_float(u & 0xffff0000u); }
;     __device__ __forceinline__ void operator()(const f32x4 (&acc)[2][2][4][2], const Unit& u, int wr, int wc, int fr, int fq) const {
; #pragma unroll
;         for (int ai = 0; ai < 2; ++ai)
; #pragma unroll
;             for (int m = 0; m < 4; ++m) {
;                 const int row = u.pm * BM + ai * HALF + wr * 64 + m * 16 + fr; const float r2 = rstd2[row];
; #pragma unroll
;                 for (int bj = 0; bj < 2; ++bj) { const size_t o = (size_t)row * DM + u.pn * BM + bj * HALF + wc * 32 + 8 * fq;
;                     const u32x4 xb = *(const u32x4*)(X1B + o);
;                     const f32x4 a = {bflo(xb.x), bfhi(xb.x), bflo(xb.y), bfhi(xb.y)}, b = {bflo(xb.z), bfhi(xb.z), bflo(xb.w), bfhi(xb.w)};
;                     *(f32x4*)(Y + o) = a + acc[ai][bj][m][0] * r2; *(f32x4*)(Y + o + 4) = b + acc[ai][bj][m][1] * r2; }
;             }
;     }
.LBB0_720:
	v_lshl_add_u32 v170, s26, 8, v131
	s_lshl_b32 s2, s45, 8
	v_readlane_b32 s30, v254, 21
	v_readlane_b32 s31, v254, 22
	v_or_b32_e32 v171, s2, v140
	v_lshl_add_u32 v172, v170, 11, v171
	v_lshlrev_b32_e32 v165, 2, v170
	v_lshlrev_b32_e32 v241, 1, v172
	v_add_u32_e32 v243, 0x10000, v241
	v_add_u32_e32 v245, 0x20000, v241
	v_add_u32_e32 v247, 0x30000, v241
	v_add_u32_e32 v249, 0x80000, v241
	v_add_u32_e32 v251, 0x90000, v241
	v_add_u32_e32 v161, 0xa0000, v241
	v_add_u32_e32 v163, 0xb0000, v241
	global_load_dword v240, v165, s[4:5] offset:0 sc1
	global_load_dwordx4 v[176:179], v241, s[66:67]
	global_load_dwordx4 v[180:183], v241, s[66:67] offset:256
	global_load_dword v242, v165, s[4:5] offset:64 sc1
	global_load_dwordx4 v[184:187], v243, s[66:67]
	global_load_dwordx4 v[188:191], v243, s[66:67] offset:256
	global_load_dword v244, v165, s[4:5] offset:128 sc1
	global_load_dwordx4 v[192:195], v245, s[66:67]
	global_load_dwordx4 v[196:199], v245, s[66:67] offset:256
	global_load_dword v246, v165, s[4:5] offset:192 sc1
	global_load_dwordx4 v[200:203], v247, s[66:67]
	global_load_dwordx4 v[204:207], v247, s[66:67] offset:256
	global_load_dword v248, v165, s[4:5] offset:512 sc1
	global_load_dwordx4 v[208:211], v249, s[66:67]
	global_load_dwordx4 v[212:215], v249, s[66:67] offset:256
	global_load_dword v250, v165, s[4:5] offset:576 sc1
	global_load_dwordx4 v[216:219], v251, s[66:67]
	global_load_dwordx4 v[220:223], v251, s[66:67] offset:256
	global_load_dword v162, v165, s[4:5] offset:640 sc1
	global_load_dwordx4 v[224:227], v161, s[66:67]
	global_load_dwordx4 v[228:231], v161, s[66:67] offset:256
	global_load_dword v164, v165, s[4:5] offset:704 sc1
	global_load_dwordx4 v[232:235], v163, s[66:67]
	global_load_dwordx4 v[236:239], v163, s[66:67] offset:256
	s_andn2_b64 vcc, exec, s[0:1]
	s_mov_b64 s[0:1], -1
	s_waitcnt vmcnt(22)
	v_lshlrev_b32_e32 v173, 1, v241
	v_lshlrev_b32_e32 v150, 16, v176
	v_and_b32_e32 v151, 0xffff0000, v176
	v_lshlrev_b32_e32 v152, 16, v177
	v_and_b32_e32 v153, 0xffff0000, v177
	v_lshlrev_b32_e32 v166, 16, v178
	v_and_b32_e32 v167, 0xffff0000, v178
	v_lshlrev_b32_e32 v168, 16, v179
	v_and_b32_e32 v169, 0xffff0000, v179
	v_pk_fma_f32 v[124:125], v[124:125], v[240:241], v[150:151] op_sel_hi:[1,0,1]
	v_pk_fma_f32 v[126:127], v[126:127], v[240:241], v[152:153] op_sel_hi:[1,0,1]
	v_pk_fma_f32 v[120:121], v[120:121], v[240:241], v[166:167] op_sel_hi:[1,0,1]
	v_pk_fma_f32 v[122:123], v[122:123], v[240:241], v[168:169] op_sel_hi:[1,0,1]
	global_store_dwordx4 v173, v[124:127], s[30:31]
	global_store_dwordx4 v173, v[120:123], s[30:31] offset:16
	s_waitcnt vmcnt(23)
	v_lshlrev_b32_e32 v150, 16, v180
	v_and_b32_e32 v151, 0xffff0000, v180
	v_lshlrev_b32_e32 v152, 16, v181
	v_and_b32_e32 v153, 0xffff0000, v181
	v_lshlrev_b32_e32 v166, 16, v182
	v_and_b32_e32 v167, 0xffff0000, v182
	v_lshlrev_b32_e32 v168, 16, v183
	v_and_b32_e32 v169, 0xffff0000, v183
	v_pk_fma_f32 v[116:117], v[116:117], v[240:241], v[150:151] op_sel_hi:[1,0,1]
	v_pk_fma_f32 v[118:119], v[118:119], v[240:241], v[152:153] op_sel_hi:[1,0,1]
	v_pk_fma_f32 v[112:113], v[112:113], v[240:241], v[166:167] op_sel_hi:[1,0,1]
	v_pk_fma_f32 v[114:115], v[114:115], v[240:241], v[168:169] op_sel_hi:[1,0,1]
	global_store_dwordx4 v173, v[116:119], s[30:31] offset:512
	global_store_dwordx4 v173, v[112:115], s[30:31] offset:528
	s_waitcnt vmcnt(23)
	v_lshlrev_b32_e32 v173, 1, v243
	v_lshlrev_b32_e32 v150, 16, v184
	v_and_b32_e32 v151, 0xffff0000, v184
	v_lshlrev_b32_e32 v152, 16, v185
	v_and_b32_e32 v153, 0xffff0000, v185
	v_lshlrev_b32_e32 v166, 16, v186
	v_and_b32_e32 v167, 0xffff0000, v186
	v_lshlrev_b32_e32 v168, 16, v187
	v_and_b32_e32 v169, 0xffff0000, v187
	v_pk_fma_f32 v[108:109], v[108:109], v[242:243], v[150:151] op_sel_hi:[1,0,1]
	v_pk_fma_f32 v[110:111], v[110:111], v[242:243], v[152:153] op_sel_hi:[1,0,1]
	v_pk_fma_f32 v[104:105], v[104:105], v[242:243], v[166:167] op_sel_hi:[1,0,1]
	v_pk_fma_f32 v[106:107], v[106:107], v[242:243], v[168:169] op_sel_hi:[1,0,1]
	global_store_dwordx4 v173, v[108:111], s[30:31]
	global_store_dwordx4 v173, v[104:107], s[30:31] offset:16
	s_waitcnt vmcnt(24)
	v_lshlrev_b32_e32 v150, 16, v188
	v_and_b32_e32 v151, 0xffff0000, v188
	v_lshlrev_b32_e32 v152, 16, v189
	v_and_b32_e32 v153, 0xffff0000, v189
	v_lshlrev_b32_e32 v166, 16, v190
	v_and_b32_e32 v167, 0xffff0000, v190
	v_lshlrev_b32_e32 v168, 16, v191
	v_and_b32_e32 v169, 0xffff0000, v191
	v_pk_fma_f32 v[100:101], v[100:101], v[242:243], v[150:151] op_sel_hi:[1,0,1]
	v_pk_fma_f32 v[102:103], v[102:103], v[242:243], v[152:153] op_sel_hi:[1,0,1]
	v_pk_fma_f32 v[96:97], v[96:97], v[242:243], v[166:167] op_sel_hi:[1,0,1]
	v_pk_fma_f32 v[98:99], v[98:99], v[242:243], v[168:169] op_sel_hi:[1,0,1]
	global_store_dwordx4 v173, v[100:103], s[30:31] offset:512
	global_store_dwordx4 v173, v[96:99], s[30:31] offset:528
	s_waitcnt vmcnt(24)
	v_lshlrev_b32_e32 v173, 1, v245
	v_lshlrev_b32_e32 v150, 16, v192
	v_and_b32_e32 v151, 0xffff0000, v192
	v_lshlrev_b32_e32 v152, 16, v193
	v_and_b32_e32 v153, 0xffff0000, v193
	v_lshlrev_b32_e32 v166, 16, v194
	v_and_b32_e32 v167, 0xffff0000, v194
	v_lshlrev_b32_e32 v168, 16, v195
	v_and_b32_e32 v169, 0xffff0000, v195
	v_pk_fma_f32 v[92:93], v[92:93], v[244:245], v[150:151] op_sel_hi:[1,0,1]
	v_pk_fma_f32 v[94:95], v[94:95], v[244:245], v[152:153] op_sel_hi:[1,0,1]
	v_pk_fma_f32 v[88:89], v[88:89], v[244:245], v[166:167] op_sel_hi:[1,0,1]
	v_pk_fma_f32 v[90:91], v[90:91], v[244:245], v[168:169] op_sel_hi:[1,0,1]
	global_store_dwordx4 v173, v[92:95], s[30:31]
	global_store_dwordx4 v173, v[88:91], s[30:31] offset:16
	s_waitcnt vmcnt(25)
; DI float bflo(unsigned u) { return __uint_as_float(u << 16); }
; DI float bfhi(unsigned u) { return __uint_as_float(u & 0xffff0000u); }
;     __device__ __forceinline__ void operator()(const f32x4 (&acc)[2][2][4][2], const Unit& u, int wr, int wc, int fr, int fq) const {
;     ...
;                 const int row = u.pm * BM + ai * HALF + wr * 64 + m * 16 + fr; const float r2 = rstd2[row];
; #pragma unroll
;                 for (int bj = 0; bj < 2; ++bj) { const size_t o = (size_t)row * DM + u.pn * BM + bj * HALF + wc * 32 + 8 * fq;
;                     const u32x4 xb = *(const u32x4*)(X1B + o);
;                     const f32x4 a = {bflo(xb.x), bfhi(xb.x), bflo(xb.y), bfhi(xb.y)}, b = {bflo(xb.z), bfhi(xb.z), bflo(xb.w), bfhi(xb.w)};
;                     *(f32x4*)(Y + o) = a + acc[ai][bj][m][0] * r2; *(f32x4*)(Y + o + 4) = b + acc[ai][bj][m][1] * r2; }
	v_lshlrev_b32_e32 v150, 16, v196
	v_and_b32_e32 v151, 0xffff0000, v196
	v_lshlrev_b32_e32 v152, 16, v197
	v_and_b32_e32 v153, 0xffff0000, v197
	v_lshlrev_b32_e32 v166, 16, v198
	v_and_b32_e32 v167, 0xffff0000, v198
	v_lshlrev_b32_e32 v168, 16, v199
	v_and_b32_e32 v169, 0xffff0000, v199
	v_pk_fma_f32 v[84:85], v[84:85], v[244:245], v[150:151] op_sel_hi:[1,0,1]
	v_pk_fma_f32 v[86:87], v[86:87], v[244:245], v[152:153] op_sel_hi:[1,0,1]
	v_pk_fma_f32 v[80:81], v[80:81], v[244:245], v[166:167] op_sel_hi:[1,0,1]
	v_pk_fma_f32 v[82:83], v[82:83], v[244:245], v[168:169] op_sel_hi:[1,0,1]
	global_store_dwordx4 v173, v[84:87], s[30:31] offset:512
	global_store_dwordx4 v173, v[80:83], s[30:31] offset:528
	s_waitcnt vmcnt(25)
	v_lshlrev_b32_e32 v173, 1, v247
	v_lshlrev_b32_e32 v150, 16, v200
	v_and_b32_e32 v151, 0xffff0000, v200
	v_lshlrev_b32_e32 v152, 16, v201
	v_and_b32_e32 v153, 0xffff0000, v201
	v_lshlrev_b32_e32 v166, 16, v202
	v_and_b32_e32 v167, 0xffff0000, v202
	v_lshlrev_b32_e32 v168, 16, v203
	v_and_b32_e32 v169, 0xffff0000, v203
	v_pk_fma_f32 v[76:77], v[76:77], v[246:247], v[150:151] op_sel_hi:[1,0,1]
	v_pk_fma_f32 v[78:79], v[78:79], v[246:247], v[152:153] op_sel_hi:[1,0,1]
	v_pk_fma_f32 v[72:73], v[72:73], v[246:247], v[166:167] op_sel_hi:[1,0,1]
	v_pk_fma_f32 v[74:75], v[74:75], v[246:247], v[168:169] op_sel_hi:[1,0,1]
	global_store_dwordx4 v173, v[76:79], s[30:31]
	global_store_dwordx4 v173, v[72:75], s[30:31] offset:16
	s_waitcnt vmcnt(26)
	v_lshlrev_b32_e32 v150, 16, v204
	v_and_b32_e32 v151, 0xffff0000, v204
	v_lshlrev_b32_e32 v152, 16, v205
	v_and_b32_e32 v153, 0xffff0000, v205
	v_lshlrev_b32_e32 v166, 16, v206
	v_and_b32_e32 v167, 0xffff0000, v206
	v_lshlrev_b32_e32 v168, 16, v207
	v_and_b32_e32 v169, 0xffff0000, v207
	v_pk_fma_f32 v[68:69], v[68:69], v[246:247], v[150:151] op_sel_hi:[1,0,1]
	v_pk_fma_f32 v[70:71], v[70:71], v[246:247], v[152:153] op_sel_hi:[1,0,1]
	v_pk_fma_f32 v[64:65], v[64:65], v[246:247], v[166:167] op_sel_hi:[1,0,1]
	v_pk_fma_f32 v[66:67], v[66:67], v[246:247], v[168:169] op_sel_hi:[1,0,1]
	global_store_dwordx4 v173, v[68:71], s[30:31] offset:512
	global_store_dwordx4 v173, v[64:67], s[30:31] offset:528
	s_waitcnt vmcnt(26)
	v_lshlrev_b32_e32 v173, 1, v249
	v_lshlrev_b32_e32 v150, 16, v208
	v_and_b32_e32 v151, 0xffff0000, v208
	v_lshlrev_b32_e32 v152, 16, v209
	v_and_b32_e32 v153, 0xffff0000, v209
	v_lshlrev_b32_e32 v166, 16, v210
	v_and_b32_e32 v167, 0xffff0000, v210
	v_lshlrev_b32_e32 v168, 16, v211
	v_and_b32_e32 v169, 0xffff0000, v211
	v_pk_fma_f32 v[60:61], v[60:61], v[248:249], v[150:151] op_sel_hi:[1,0,1]
	v_pk_fma_f32 v[62:63], v[62:63], v[248:249], v[152:153] op_sel_hi:[1,0,1]
	v_pk_fma_f32 v[56:57], v[56:57], v[248:249], v[166:167] op_sel_hi:[1,0,1]
	v_pk_fma_f32 v[58:59], v[58:59], v[248:249], v[168:169] op_sel_hi:[1,0,1]
	global_store_dwordx4 v173, v[60:63], s[30:31]
	global_store_dwordx4 v173, v[56:59], s[30:31] offset:16
	s_waitcnt vmcnt(27)
	v_lshlrev_b32_e32 v150, 16, v212
	v_and_b32_e32 v151, 0xffff0000, v212
	v_lshlrev_b32_e32 v152, 16, v213
	v_and_b32_e32 v153, 0xffff0000, v213
	v_lshlrev_b32_e32 v166, 16, v214
	v_and_b32_e32 v167, 0xffff0000, v214
	v_lshlrev_b32_e32 v168, 16, v215
	v_and_b32_e32 v169, 0xffff0000, v215
	v_pk_fma_f32 v[52:53], v[52:53], v[248:249], v[150:151] op_sel_hi:[1,0,1]
	v_pk_fma_f32 v[54:55], v[54:55], v[248:249], v[152:153] op_sel_hi:[1,0,1]
	v_pk_fma_f32 v[48:49], v[48:49], v[248:249], v[166:167] op_sel_hi:[1,0,1]
	v_pk_fma_f32 v[50:51], v[50:51], v[248:249], v[168:169] op_sel_hi:[1,0,1]
	global_store_dwordx4 v173, v[52:55], s[30:31] offset:512
	global_store_dwordx4 v173, v[48:51], s[30:31] offset:528
	s_waitcnt vmcnt(27)
	v_lshlrev_b32_e32 v173, 1, v251
	v_lshlrev_b32_e32 v150, 16, v216
	v_and_b32_e32 v151, 0xffff0000, v216
	v_lshlrev_b32_e32 v152, 16, v217
	v_and_b32_e32 v153, 0xffff0000, v217
	v_lshlrev_b32_e32 v166, 16, v218
	v_and_b32_e32 v167, 0xffff0000, v218
	v_lshlrev_b32_e32 v168, 16, v219
	v_and_b32_e32 v169, 0xffff0000, v219
	v_pk_fma_f32 v[44:45], v[44:45], v[250:251], v[150:151] op_sel_hi:[1,0,1]
	v_pk_fma_f32 v[46:47], v[46:47], v[250:251], v[152:153] op_sel_hi:[1,0,1]
	v_pk_fma_f32 v[40:41], v[40:41], v[250:251], v[166:167] op_sel_hi:[1,0,1]
	v_pk_fma_f32 v[42:43], v[42:43], v[250:251], v[168:169] op_sel_hi:[1,0,1]
	global_store_dwordx4 v173, v[44:47], s[30:31]
	global_store_dwordx4 v173, v[40:43], s[30:31] offset:16
	s_waitcnt vmcnt(28)
; DI float bflo(unsigned u) { return __uint_as_float(u << 16); }
; DI float bfhi(unsigned u) { return __uint_as_float(u & 0xffff0000u); }
; #define PG8_BAR __builtin_amdgcn_s_barrier()
;     __device__ __forceinline__ void operator()(const f32x4 (&acc)[2][2][4][2], const Unit& u, int wr, int wc, int fr, int fq) const {
;     ...
;                 for (int bj = 0; bj < 2; ++bj) { const size_t o = (size_t)row * DM + u.pn * BM + bj * HALF + wc * 32 + 8 * fq;
;                     const u32x4 xb = *(const u32x4*)(X1B + o);
;                     const f32x4 a = {bflo(xb.x), bfhi(xb.x), bflo(xb.y), bfhi(xb.y)}, b = {bflo(xb.z), bfhi(xb.z), bflo(xb.w), bfhi(xb.w)};
;                     *(f32x4*)(Y + o) = a + acc[ai][bj][m][0] * r2; *(f32x4*)(Y + o + 4) = b + acc[ai][bj][m][1] * r2; }
; template <class Epi, class Sched, bool ALIGN_EPI = false, bool SP2 = false>
; __device__ __forceinline__ void gemm_phase(PG8_LAS unsigned char* lds, const Gemm g, const Sched& S, const Epi& E) {
;     ...
;         if (!has_next) break;
; #pragma unroll
;         for (int a = 0; a < 2; ++a)
; #pragma unroll
;             for (int b = 0; b < 2; ++b)
; #pragma unroll
;                 for (int m = 0; m < 4; ++m)
; #pragma unroll
;                     for (int n = 0; n < 2; ++n) acc[a][b][m][n] = (f32x4){0.f, 0.f, 0.f, 0.f};
;         cur = nxt; cA = nA; cB = nB; ++ui;
;         if constexpr (ALIGN_EPI) { if (wr == 1) PG8_BAR; }
;     }
	v_lshlrev_b32_e32 v150, 16, v220
	v_and_b32_e32 v151, 0xffff0000, v220
	v_lshlrev_b32_e32 v152, 16, v221
	v_and_b32_e32 v153, 0xffff0000, v221
	v_lshlrev_b32_e32 v166, 16, v222
	v_and_b32_e32 v167, 0xffff0000, v222
	v_lshlrev_b32_e32 v168, 16, v223
	v_and_b32_e32 v169, 0xffff0000, v223
	v_pk_fma_f32 v[36:37], v[36:37], v[250:251], v[150:151] op_sel_hi:[1,0,1]
	v_pk_fma_f32 v[38:39], v[38:39], v[250:251], v[152:153] op_sel_hi:[1,0,1]
	v_pk_fma_f32 v[32:33], v[32:33], v[250:251], v[166:167] op_sel_hi:[1,0,1]
	v_pk_fma_f32 v[34:35], v[34:35], v[250:251], v[168:169] op_sel_hi:[1,0,1]
	global_store_dwordx4 v173, v[36:39], s[30:31] offset:512
	global_store_dwordx4 v173, v[32:35], s[30:31] offset:528
	s_waitcnt vmcnt(28)
	v_lshlrev_b32_e32 v173, 1, v161
	v_lshlrev_b32_e32 v150, 16, v224
	v_and_b32_e32 v151, 0xffff0000, v224
	v_lshlrev_b32_e32 v152, 16, v225
	v_and_b32_e32 v153, 0xffff0000, v225
	v_lshlrev_b32_e32 v166, 16, v226
	v_and_b32_e32 v167, 0xffff0000, v226
	v_lshlrev_b32_e32 v168, 16, v227
	v_and_b32_e32 v169, 0xffff0000, v227
	v_pk_fma_f32 v[28:29], v[28:29], v[162:163], v[150:151] op_sel_hi:[1,0,1]
	v_pk_fma_f32 v[30:31], v[30:31], v[162:163], v[152:153] op_sel_hi:[1,0,1]
	v_pk_fma_f32 v[24:25], v[24:25], v[162:163], v[166:167] op_sel_hi:[1,0,1]
	v_pk_fma_f32 v[26:27], v[26:27], v[162:163], v[168:169] op_sel_hi:[1,0,1]
	global_store_dwordx4 v173, v[28:31], s[30:31]
	global_store_dwordx4 v173, v[24:27], s[30:31] offset:16
	s_waitcnt vmcnt(29)
	v_lshlrev_b32_e32 v150, 16, v228
	v_and_b32_e32 v151, 0xffff0000, v228
	v_lshlrev_b32_e32 v152, 16, v229
	v_and_b32_e32 v153, 0xffff0000, v229
	v_lshlrev_b32_e32 v166, 16, v230
	v_and_b32_e32 v167, 0xffff0000, v230
	v_lshlrev_b32_e32 v168, 16, v231
	v_and_b32_e32 v169, 0xffff0000, v231
	v_pk_fma_f32 v[20:21], v[20:21], v[162:163], v[150:151] op_sel_hi:[1,0,1]
	v_pk_fma_f32 v[22:23], v[22:23], v[162:163], v[152:153] op_sel_hi:[1,0,1]
	v_pk_fma_f32 v[16:17], v[16:17], v[162:163], v[166:167] op_sel_hi:[1,0,1]
	v_pk_fma_f32 v[18:19], v[18:19], v[162:163], v[168:169] op_sel_hi:[1,0,1]
	global_store_dwordx4 v173, v[20:23], s[30:31] offset:512
	global_store_dwordx4 v173, v[16:19], s[30:31] offset:528
	s_waitcnt vmcnt(29)
	v_lshlrev_b32_e32 v173, 1, v163
	v_lshlrev_b32_e32 v150, 16, v232
	v_and_b32_e32 v151, 0xffff0000, v232
	v_lshlrev_b32_e32 v152, 16, v233
	v_and_b32_e32 v153, 0xffff0000, v233
	v_lshlrev_b32_e32 v166, 16, v234
	v_and_b32_e32 v167, 0xffff0000, v234
	v_lshlrev_b32_e32 v168, 16, v235
	v_and_b32_e32 v169, 0xffff0000, v235
	v_pk_fma_f32 v[12:13], v[12:13], v[164:165], v[150:151] op_sel_hi:[1,0,1]
	v_pk_fma_f32 v[14:15], v[14:15], v[164:165], v[152:153] op_sel_hi:[1,0,1]
	v_pk_fma_f32 v[8:9], v[8:9], v[164:165], v[166:167] op_sel_hi:[1,0,1]
	v_pk_fma_f32 v[10:11], v[10:11], v[164:165], v[168:169] op_sel_hi:[1,0,1]
	global_store_dwordx4 v173, v[12:15], s[30:31]
	global_store_dwordx4 v173, v[8:11], s[30:31] offset:16
	s_waitcnt vmcnt(30)
	v_lshlrev_b32_e32 v150, 16, v236
	v_and_b32_e32 v151, 0xffff0000, v236
	v_lshlrev_b32_e32 v152, 16, v237
	v_and_b32_e32 v153, 0xffff0000, v237
	v_lshlrev_b32_e32 v166, 16, v238
	v_and_b32_e32 v167, 0xffff0000, v238
	v_lshlrev_b32_e32 v168, 16, v239
	v_and_b32_e32 v169, 0xffff0000, v239
	v_pk_fma_f32 v[4:5], v[4:5], v[164:165], v[150:151] op_sel_hi:[1,0,1]
	v_pk_fma_f32 v[6:7], v[6:7], v[164:165], v[152:153] op_sel_hi:[1,0,1]
	v_pk_fma_f32 v[0:1], v[0:1], v[164:165], v[166:167] op_sel_hi:[1,0,1]
	v_pk_fma_f32 v[2:3], v[2:3], v[164:165], v[168:169] op_sel_hi:[1,0,1]
	global_store_dwordx4 v173, v[4:7], s[30:31] offset:512
	global_store_dwordx4 v173, v[0:3], s[30:31] offset:528
	s_cbranch_vccnz .LBB0_709
	s_andn2_b64 vcc, exec, s[12:13]
	s_cbranch_vccnz .LBB0_708
	s_barrier
	s_branch .LBB0_708

; __global__ void __launch_bounds__(512, 2) fwd_kernel(Args a) {
;     ...
;         for (int e = bx * 512 + tid; e < NS * DM / 4; e += G * 512) {
;             const int row = e >> 9; float* p = out + O_Y + (size_t)LP * DM + (size_t)e * 4;
;             const f32x4 s = (*(const f32x4*)(SLAB + (size_t)e * 4) + *(const f32x4*)(SLAB + (size_t)NS * DM + (size_t)e * 4)) + (*(const f32x4*)(SLAB + (size_t)2 * NS * DM + (size_t)e * 4) + *(const f32x4*)(SLAB + (size_t)3 * NS * DM + (size_t)e * 4));
;             *(f32x4*)p = *(const f32x4*)p + s * RSTD2[LP + row];
;         }
.LBB0_784:
	v_lshl_add_u64 v[16:17], s[60:61], 0, v[2:3]
	v_add_co_u32_e32 v18, vcc, 0x13c00000, v16
	v_ashrrev_i32_e32 v8, 9, v0
	s_nop 0
	v_addc_co_u32_e32 v19, vcc, 0, v17, vcc
	v_add_co_u32_e32 v20, vcc, 0x13d00000, v16
	v_ashrrev_i32_e32 v9, 31, v8
	s_nop 0
	v_addc_co_u32_e32 v21, vcc, 0, v17, vcc
	v_add_co_u32_e32 v28, vcc, 0x13e00000, v16
	v_lshl_add_u64 v[24:25], s[0:1], 0, v[2:3]
	s_nop 0
	v_addc_co_u32_e32 v29, vcc, 0, v17, vcc
	v_add_co_u32_e32 v30, vcc, 0x13f00000, v16
	v_lshl_add_u64 v[26:27], v[8:9], 2, s[4:5]
	s_nop 0
	v_addc_co_u32_e32 v31, vcc, 0, v17, vcc
	global_load_dwordx4 v[4:7], v[24:25], off
	s_waitcnt lgkmcnt(0)
	global_load_dwordx4 v[8:11], v[18:19], off
	global_load_dwordx4 v[12:15], v[20:21], off
	v_add_co_u32_e32 v26, vcc, s3, v26
	global_load_dwordx4 v[16:19], v[28:29], off
	global_load_dwordx4 v[20:23], v[30:31], off
	v_addc_co_u32_e32 v27, vcc, 0, v27, vcc
	global_load_dword v26, v[26:27], off sc1
	v_add_u32_e32 v0, s2, v0
	v_cmp_lt_i32_e32 vcc, s10, v0
	v_lshl_add_u64 v[2:3], v[2:3], 0, s[6:7]
	s_or_b64 s[8:9], vcc, s[8:9]
	s_waitcnt vmcnt(0)
	v_pk_add_f32 v[10:11], v[10:11], v[14:15]
	v_pk_add_f32 v[8:9], v[8:9], v[12:13]
	v_pk_add_f32 v[12:13], v[18:19], v[22:23]
	v_pk_add_f32 v[14:15], v[16:17], v[20:21]
	v_pk_add_f32 v[10:11], v[10:11], v[12:13]
	v_pk_add_f32 v[8:9], v[8:9], v[14:15]
	v_pk_fma_f32 v[6:7], v[10:11], v[26:27], v[6:7] op_sel_hi:[1,0,1]
	v_pk_fma_f32 v[4:5], v[8:9], v[26:27], v[4:5] op_sel_hi:[1,0,1]
	global_store_dwordx4 v[24:25], v[4:7], off
	s_andn2_b64 exec, exec, s[8:9]
	s_cbranch_execnz .LBB0_784
